# P14 final rmsnorm loop rewritten: g hoisted into registers once, row loads double-buffered with counted vmcnt (no per-chunk g reload + vmcnt(0))
# baseline (speedup 1.0000x reference)
; #define lane lane_id()
; template <bool BF>
; __device__ __forceinline__ void rms_row(const float* xrow, const float* g, void* orow, int lane) {
;     const f32x4* xr = (const f32x4*)xrow + lane; const f32x4* gr = (const f32x4*)g + lane;
;     f32x4 v[8]; float s = 0.f;
; #pragma unroll
;     for (int j = 0; j < 8; ++j) { v[j] = xr[64 * j]; s += (v[j].x * v[j].x + v[j].y * v[j].y) + (v[j].z * v[j].z + v[j].w * v[j].w); }
; __global__ void __launch_bounds__(512, 2) mega_fwd(Args args) {
;     ...
;     if (IN(14)) { for (int m = gw; m < TOK; m += NGW) rms_row<false>(out + (size_t)m * DM, args.in[I_NFIN], out + (size_t)m * DM, lane); }
.LBB0_1831:
	v_mbcnt_lo_u32_b32 v0, -1, 0
	v_mbcnt_hi_u32_b32 v0, -1, v0
	v_and_b32_e32 v0, 63, v0
	v_lshlrev_b32_e32 v0, 4, v0
	s_waitcnt lgkmcnt(0)
	s_add_u32 s8, s0, 0x1000
	s_addc_u32 s9, s1, 0
	global_load_dwordx4 v[64:67], v0, s[0:1] offset:0
	global_load_dwordx4 v[68:71], v0, s[0:1] offset:1024
	global_load_dwordx4 v[72:75], v0, s[0:1] offset:2048
	global_load_dwordx4 v[76:79], v0, s[0:1] offset:3072
	global_load_dwordx4 v[80:83], v0, s[8:9] offset:0
	global_load_dwordx4 v[84:87], v0, s[8:9] offset:1024
	global_load_dwordx4 v[88:91], v0, s[8:9] offset:2048
	global_load_dwordx4 v[92:95], v0, s[8:9] offset:3072
	global_load_dwordx4 v[4:7], v0, s[2:3] offset:-4096
	global_load_dwordx4 v[8:11], v0, s[2:3] offset:-3072
	global_load_dwordx4 v[12:15], v0, s[2:3] offset:-2048
	global_load_dwordx4 v[16:19], v0, s[2:3] offset:-1024
	global_load_dwordx4 v[20:23], v0, s[2:3] offset:0
	global_load_dwordx4 v[24:27], v0, s[2:3] offset:1024
	global_load_dwordx4 v[28:31], v0, s[2:3] offset:2048
	global_load_dwordx4 v[32:35], v0, s[2:3] offset:3072
	s_waitcnt vmcnt(0)
	s_branch .Lp14_bodyA

; __device__ __forceinline__ unsigned cvtpk(float lo, float hi) { unsigned r; asm volatile("v_cvt_pk_bf16_f32 %0, %1, %2" : "=v"(r) : "v"(lo), "v"(hi)); return r; }
; #define lane lane_id()
; template <bool BF>
; __device__ __forceinline__ void rms_row(const float* xrow, const float* g, void* orow, int lane) {
;     const f32x4* xr = (const f32x4*)xrow + lane; const f32x4* gr = (const f32x4*)g + lane;
;     f32x4 v[8]; float s = 0.f;
; #pragma unroll
;     for (int j = 0; j < 8; ++j) { v[j] = xr[64 * j]; s += (v[j].x * v[j].x + v[j].y * v[j].y) + (v[j].z * v[j].z + v[j].w * v[j].w); }
;     const float rstd = rsqrtf(wave_sum(s) * (1.f / DM) + RMS_EPS);
; #pragma unroll
;     for (int j = 0; j < 8; ++j) { const f32x4 gg = gr[64 * j]; const f32x4 y = v[j] * rstd * gg;
;         if (BF) { u32x2 w; w.x = cvtpk(y.x, y.y); w.y = cvtpk(y.z, y.w); ((u32x2*)orow)[64 * j + lane] = w; }
;         else ((f32x4*)orow)[64 * j + lane] = y; }
; }
.Lp14_bodyA:
	s_add_i32 s13, s13, s14
	s_add_u32 s10, s2, s4
	s_addc_u32 s11, s3, s5
	s_cmp_lt_i32 s13, 0x8000
	s_cbranch_scc0 .Lp14_nonextA
	global_load_dwordx4 v[100:103], v0, s[10:11] offset:-4096
	global_load_dwordx4 v[104:107], v0, s[10:11] offset:-3072
	global_load_dwordx4 v[108:111], v0, s[10:11] offset:-2048
	global_load_dwordx4 v[112:115], v0, s[10:11] offset:-1024
	global_load_dwordx4 v[116:119], v0, s[10:11] offset:0
	global_load_dwordx4 v[120:123], v0, s[10:11] offset:1024
	global_load_dwordx4 v[124:127], v0, s[10:11] offset:2048
	global_load_dwordx4 v[128:131], v0, s[10:11] offset:3072
.Lp14_nonextA:
	v_mul_f32_e32 v3, v5, v5
	v_mul_f32_e32 v40, v7, v7
	v_mul_f32_e32 v41, v9, v9
	v_mul_f32_e32 v42, v11, v11
	v_mul_f32_e32 v43, v13, v13
	v_mul_f32_e32 v44, v15, v15
	v_fmac_f32_e32 v3, v4, v4
	v_fmac_f32_e32 v40, v6, v6
	v_fmac_f32_e32 v41, v8, v8
	v_fmac_f32_e32 v42, v10, v10
	v_mul_f32_e32 v45, v17, v17
	v_mul_f32_e32 v46, v19, v19
	v_fmac_f32_e32 v43, v12, v12
	v_fmac_f32_e32 v44, v14, v14
	v_add_f32_e32 v3, v3, v40
	v_add_f32_e32 v40, v41, v42
	v_mul_f32_e32 v47, v21, v21
	v_mul_f32_e32 v48, v23, v23
	v_fmac_f32_e32 v45, v16, v16
	v_fmac_f32_e32 v46, v18, v18
	v_add_f32_e32 v41, v43, v44
	v_add_f32_e32 v3, v3, v40
	v_mul_f32_e32 v49, v25, v25
	v_mul_f32_e32 v50, v27, v27
	v_fmac_f32_e32 v47, v20, v20
	v_fmac_f32_e32 v48, v22, v22
	v_add_f32_e32 v42, v45, v46
	v_add_f32_e32 v3, v3, v41
	v_mul_f32_e32 v51, v29, v29
	v_mul_f32_e32 v52, v31, v31
	v_fmac_f32_e32 v49, v24, v24
	v_fmac_f32_e32 v50, v26, v26
	v_add_f32_e32 v43, v47, v48
	v_add_f32_e32 v3, v3, v42
	v_mul_f32_e32 v53, v33, v33
	v_mul_f32_e32 v54, v35, v35
	v_fmac_f32_e32 v51, v28, v28
	v_fmac_f32_e32 v52, v30, v30
	v_add_f32_e32 v44, v49, v50
	v_add_f32_e32 v3, v3, v43
	v_fmac_f32_e32 v53, v32, v32
	v_fmac_f32_e32 v54, v34, v34
	v_add_f32_e32 v45, v51, v52
	v_add_f32_e32 v3, v3, v44
	v_add_f32_e32 v46, v53, v54
	v_add_f32_e32 v3, v3, v45
	v_add_f32_e32 v3, v3, v46
	s_nop 1
	v_add_f32_dpp v3, v3, v3 quad_perm:[1,0,3,2] row_mask:0xf bank_mask:0xf bound_ctrl:1
	s_nop 1
	v_add_f32_dpp v3, v3, v3 quad_perm:[2,3,0,1] row_mask:0xf bank_mask:0xf bound_ctrl:1
	s_nop 1
	v_add_f32_dpp v3, v3, v3 row_half_mirror row_mask:0xf bank_mask:0xf bound_ctrl:1
	s_nop 1
	v_add_f32_dpp v3, v3, v3 row_mirror row_mask:0xf bank_mask:0xf bound_ctrl:1
	v_mov_b32_e32 v40, v3
	s_nop 1
	v_permlane16_swap_b32_e32 v3, v40
	v_add_f32_e32 v3, v3, v40
	v_mov_b32_e32 v40, v3
	s_nop 1
	v_permlane32_swap_b32_e32 v3, v40
	v_add_f32_e32 v3, v3, v40
	v_fmamk_f32 v3, v3, 0x3a000000, v2
	v_mul_f32_e32 v40, 0x4b800000, v3
	v_cmp_gt_f32_e32 vcc, s6, v3
	s_nop 1
	v_cndmask_b32_e32 v3, v3, v40, vcc
	v_rsq_f32_e32 v3, v3
	s_nop 0
	v_mul_f32_e32 v40, 0x45800000, v3
	v_cndmask_b32_e32 v40, v3, v40, vcc
	v_pk_mul_f32 v[4:5], v[4:5], v[40:41] op_sel_hi:[1,0]
	v_pk_mul_f32 v[6:7], v[6:7], v[40:41] op_sel_hi:[1,0]
	v_pk_mul_f32 v[4:5], v[64:65], v[4:5]
	v_pk_mul_f32 v[6:7], v[66:67], v[6:7]
	global_store_dwordx4 v0, v[4:7], s[2:3] offset:-4096
	v_pk_mul_f32 v[8:9], v[8:9], v[40:41] op_sel_hi:[1,0]
	v_pk_mul_f32 v[10:11], v[10:11], v[40:41] op_sel_hi:[1,0]
	v_pk_mul_f32 v[8:9], v[68:69], v[8:9]
	v_pk_mul_f32 v[10:11], v[70:71], v[10:11]
	global_store_dwordx4 v0, v[8:11], s[2:3] offset:-3072
	v_pk_mul_f32 v[12:13], v[12:13], v[40:41] op_sel_hi:[1,0]
	v_pk_mul_f32 v[14:15], v[14:15], v[40:41] op_sel_hi:[1,0]
	v_pk_mul_f32 v[12:13], v[72:73], v[12:13]
	v_pk_mul_f32 v[14:15], v[74:75], v[14:15]
	global_store_dwordx4 v0, v[12:15], s[2:3] offset:-2048
	v_pk_mul_f32 v[16:17], v[16:17], v[40:41] op_sel_hi:[1,0]
	v_pk_mul_f32 v[18:19], v[18:19], v[40:41] op_sel_hi:[1,0]
	v_pk_mul_f32 v[16:17], v[76:77], v[16:17]
	v_pk_mul_f32 v[18:19], v[78:79], v[18:19]
	global_store_dwordx4 v0, v[16:19], s[2:3] offset:-1024
	v_pk_mul_f32 v[20:21], v[20:21], v[40:41] op_sel_hi:[1,0]
	v_pk_mul_f32 v[22:23], v[22:23], v[40:41] op_sel_hi:[1,0]
	v_pk_mul_f32 v[20:21], v[80:81], v[20:21]
	v_pk_mul_f32 v[22:23], v[82:83], v[22:23]
	global_store_dwordx4 v0, v[20:23], s[2:3] offset:0
	v_pk_mul_f32 v[24:25], v[24:25], v[40:41] op_sel_hi:[1,0]
	v_pk_mul_f32 v[26:27], v[26:27], v[40:41] op_sel_hi:[1,0]
	v_pk_mul_f32 v[24:25], v[84:85], v[24:25]
	v_pk_mul_f32 v[26:27], v[86:87], v[26:27]
	global_store_dwordx4 v0, v[24:27], s[2:3] offset:1024
	v_pk_mul_f32 v[28:29], v[28:29], v[40:41] op_sel_hi:[1,0]
	v_pk_mul_f32 v[30:31], v[30:31], v[40:41] op_sel_hi:[1,0]
	v_pk_mul_f32 v[28:29], v[88:89], v[28:29]
	v_pk_mul_f32 v[30:31], v[90:91], v[30:31]
	global_store_dwordx4 v0, v[28:31], s[2:3] offset:2048
	v_pk_mul_f32 v[32:33], v[32:33], v[40:41] op_sel_hi:[1,0]
	v_pk_mul_f32 v[34:35], v[34:35], v[40:41] op_sel_hi:[1,0]
	v_pk_mul_f32 v[32:33], v[92:93], v[32:33]
	v_pk_mul_f32 v[34:35], v[94:95], v[34:35]
	global_store_dwordx4 v0, v[32:35], s[2:3] offset:3072
	s_cmp_lt_i32 s13, 0x8000
	s_cbranch_scc0 .Lp14_done
	s_waitcnt vmcnt(8)
	s_add_i32 s13, s13, s14
	s_add_u32 s2, s10, s4
	s_addc_u32 s3, s11, s5
	s_cmp_lt_i32 s13, 0x8000
	s_cbranch_scc0 .Lp14_nonextB
	global_load_dwordx4 v[4:7], v0, s[2:3] offset:-4096
	global_load_dwordx4 v[8:11], v0, s[2:3] offset:-3072
	global_load_dwordx4 v[12:15], v0, s[2:3] offset:-2048
	global_load_dwordx4 v[16:19], v0, s[2:3] offset:-1024
	global_load_dwordx4 v[20:23], v0, s[2:3] offset:0
	global_load_dwordx4 v[24:27], v0, s[2:3] offset:1024
	global_load_dwordx4 v[28:31], v0, s[2:3] offset:2048
	global_load_dwordx4 v[32:35], v0, s[2:3] offset:3072
; __device__ __forceinline__ unsigned cvtpk(float lo, float hi) { unsigned r; asm volatile("v_cvt_pk_bf16_f32 %0, %1, %2" : "=v"(r) : "v"(lo), "v"(hi)); return r; }
; #define lane lane_id()
; template <bool BF>
; __device__ __forceinline__ void rms_row(const float* xrow, const float* g, void* orow, int lane) {
;     const f32x4* xr = (const f32x4*)xrow + lane; const f32x4* gr = (const f32x4*)g + lane;
;     f32x4 v[8]; float s = 0.f;
; #pragma unroll
;     for (int j = 0; j < 8; ++j) { v[j] = xr[64 * j]; s += (v[j].x * v[j].x + v[j].y * v[j].y) + (v[j].z * v[j].z + v[j].w * v[j].w); }
;     const float rstd = rsqrtf(wave_sum(s) * (1.f / DM) + RMS_EPS);
; #pragma unroll
;     for (int j = 0; j < 8; ++j) { const f32x4 gg = gr[64 * j]; const f32x4 y = v[j] * rstd * gg;
;         if (BF) { u32x2 w; w.x = cvtpk(y.x, y.y); w.y = cvtpk(y.z, y.w); ((u32x2*)orow)[64 * j + lane] = w; }
;         else ((f32x4*)orow)[64 * j + lane] = y; }
; }
; __global__ void __launch_bounds__(512, 2) mega_fwd(Args args) {
;     ...
;     if (IN(14)) { for (int m = gw; m < TOK; m += NGW) rms_row<false>(out + (size_t)m * DM, args.in[I_NFIN], out + (size_t)m * DM, lane); }
.Lp14_nonextB:
	v_mul_f32_e32 v3, v101, v101
	v_mul_f32_e32 v40, v103, v103
	v_mul_f32_e32 v41, v105, v105
	v_mul_f32_e32 v42, v107, v107
	v_mul_f32_e32 v43, v109, v109
	v_mul_f32_e32 v44, v111, v111
	v_fmac_f32_e32 v3, v100, v100
	v_fmac_f32_e32 v40, v102, v102
	v_fmac_f32_e32 v41, v104, v104
	v_fmac_f32_e32 v42, v106, v106
	v_mul_f32_e32 v45, v113, v113
	v_mul_f32_e32 v46, v115, v115
	v_fmac_f32_e32 v43, v108, v108
	v_fmac_f32_e32 v44, v110, v110
	v_add_f32_e32 v3, v3, v40
	v_add_f32_e32 v40, v41, v42
	v_mul_f32_e32 v47, v117, v117
	v_mul_f32_e32 v48, v119, v119
	v_fmac_f32_e32 v45, v112, v112
	v_fmac_f32_e32 v46, v114, v114
	v_add_f32_e32 v41, v43, v44
	v_add_f32_e32 v3, v3, v40
	v_mul_f32_e32 v49, v121, v121
	v_mul_f32_e32 v50, v123, v123
	v_fmac_f32_e32 v47, v116, v116
	v_fmac_f32_e32 v48, v118, v118
	v_add_f32_e32 v42, v45, v46
	v_add_f32_e32 v3, v3, v41
	v_mul_f32_e32 v51, v125, v125
	v_mul_f32_e32 v52, v127, v127
	v_fmac_f32_e32 v49, v120, v120
	v_fmac_f32_e32 v50, v122, v122
	v_add_f32_e32 v43, v47, v48
	v_add_f32_e32 v3, v3, v42
	v_mul_f32_e32 v53, v129, v129
	v_mul_f32_e32 v54, v131, v131
	v_fmac_f32_e32 v51, v124, v124
	v_fmac_f32_e32 v52, v126, v126
	v_add_f32_e32 v44, v49, v50
	v_add_f32_e32 v3, v3, v43
	v_fmac_f32_e32 v53, v128, v128
	v_fmac_f32_e32 v54, v130, v130
	v_add_f32_e32 v45, v51, v52
	v_add_f32_e32 v3, v3, v44
	v_add_f32_e32 v46, v53, v54
	v_add_f32_e32 v3, v3, v45
	v_add_f32_e32 v3, v3, v46
	s_nop 1
	v_add_f32_dpp v3, v3, v3 quad_perm:[1,0,3,2] row_mask:0xf bank_mask:0xf bound_ctrl:1
	s_nop 1
	v_add_f32_dpp v3, v3, v3 quad_perm:[2,3,0,1] row_mask:0xf bank_mask:0xf bound_ctrl:1
	s_nop 1
	v_add_f32_dpp v3, v3, v3 row_half_mirror row_mask:0xf bank_mask:0xf bound_ctrl:1
	s_nop 1
	v_add_f32_dpp v3, v3, v3 row_mirror row_mask:0xf bank_mask:0xf bound_ctrl:1
	v_mov_b32_e32 v40, v3
	s_nop 1
	v_permlane16_swap_b32_e32 v3, v40
	v_add_f32_e32 v3, v3, v40
	v_mov_b32_e32 v40, v3
	s_nop 1
	v_permlane32_swap_b32_e32 v3, v40
	v_add_f32_e32 v3, v3, v40
	v_fmamk_f32 v3, v3, 0x3a000000, v2
	v_mul_f32_e32 v40, 0x4b800000, v3
	v_cmp_gt_f32_e32 vcc, s6, v3
	s_nop 1
	v_cndmask_b32_e32 v3, v3, v40, vcc
	v_rsq_f32_e32 v3, v3
	s_nop 0
	v_mul_f32_e32 v40, 0x45800000, v3
	v_cndmask_b32_e32 v40, v3, v40, vcc
	v_pk_mul_f32 v[100:101], v[100:101], v[40:41] op_sel_hi:[1,0]
	v_pk_mul_f32 v[102:103], v[102:103], v[40:41] op_sel_hi:[1,0]
	v_pk_mul_f32 v[100:101], v[64:65], v[100:101]
	v_pk_mul_f32 v[102:103], v[66:67], v[102:103]
	global_store_dwordx4 v0, v[100:103], s[10:11] offset:-4096
	v_pk_mul_f32 v[104:105], v[104:105], v[40:41] op_sel_hi:[1,0]
	v_pk_mul_f32 v[106:107], v[106:107], v[40:41] op_sel_hi:[1,0]
	v_pk_mul_f32 v[104:105], v[68:69], v[104:105]
	v_pk_mul_f32 v[106:107], v[70:71], v[106:107]
	global_store_dwordx4 v0, v[104:107], s[10:11] offset:-3072
	v_pk_mul_f32 v[108:109], v[108:109], v[40:41] op_sel_hi:[1,0]
	v_pk_mul_f32 v[110:111], v[110:111], v[40:41] op_sel_hi:[1,0]
	v_pk_mul_f32 v[108:109], v[72:73], v[108:109]
	v_pk_mul_f32 v[110:111], v[74:75], v[110:111]
	global_store_dwordx4 v0, v[108:111], s[10:11] offset:-2048
	v_pk_mul_f32 v[112:113], v[112:113], v[40:41] op_sel_hi:[1,0]
	v_pk_mul_f32 v[114:115], v[114:115], v[40:41] op_sel_hi:[1,0]
	v_pk_mul_f32 v[112:113], v[76:77], v[112:113]
	v_pk_mul_f32 v[114:115], v[78:79], v[114:115]
	global_store_dwordx4 v0, v[112:115], s[10:11] offset:-1024
	v_pk_mul_f32 v[116:117], v[116:117], v[40:41] op_sel_hi:[1,0]
	v_pk_mul_f32 v[118:119], v[118:119], v[40:41] op_sel_hi:[1,0]
	v_pk_mul_f32 v[116:117], v[80:81], v[116:117]
	v_pk_mul_f32 v[118:119], v[82:83], v[118:119]
	global_store_dwordx4 v0, v[116:119], s[10:11] offset:0
	v_pk_mul_f32 v[120:121], v[120:121], v[40:41] op_sel_hi:[1,0]
	v_pk_mul_f32 v[122:123], v[122:123], v[40:41] op_sel_hi:[1,0]
	v_pk_mul_f32 v[120:121], v[84:85], v[120:121]
	v_pk_mul_f32 v[122:123], v[86:87], v[122:123]
	global_store_dwordx4 v0, v[120:123], s[10:11] offset:1024
	v_pk_mul_f32 v[124:125], v[124:125], v[40:41] op_sel_hi:[1,0]
	v_pk_mul_f32 v[126:127], v[126:127], v[40:41] op_sel_hi:[1,0]
	v_pk_mul_f32 v[124:125], v[88:89], v[124:125]
	v_pk_mul_f32 v[126:127], v[90:91], v[126:127]
	global_store_dwordx4 v0, v[124:127], s[10:11] offset:2048
	v_pk_mul_f32 v[128:129], v[128:129], v[40:41] op_sel_hi:[1,0]
	v_pk_mul_f32 v[130:131], v[130:131], v[40:41] op_sel_hi:[1,0]
	v_pk_mul_f32 v[128:129], v[92:93], v[128:129]
	v_pk_mul_f32 v[130:131], v[94:95], v[130:131]
	global_store_dwordx4 v0, v[128:131], s[10:11] offset:3072
	s_cmp_lt_i32 s13, 0x8000
	s_cbranch_scc1 .Lp14_loopA
.Lp14_done:
.LBB0_1832:
	s_endpgm
